# LDS bank conflicts: transposed-V staging in the GLA phases re-assigned so a lane row writes consecutive dwords (16-way conflict removed)
# speedup vs baseline: 1.0104x; 1.0049x over previous
.Lswap_ga_entry:
	s_cbranch_vccz .Lswap_ga_exit
	s_load_dwordx2 s[6:7], s[6:7], 0x80
	v_ashrrev_i32_e32 v3, 8, v21
	v_lshlrev_b32_e32 v0, 1, v21
	v_and_b32_e32 v20, 62, v0
	v_add_u32_e32 v0, s94, v3
	v_bfe_u32 v31, v0, 7, 2
	v_lshlrev_b32_e32 v1, 4, v0
	v_lshlrev_b32_e32 v0, 6, v0
	v_bfe_u32 v30, v21, 5, 3
	v_and_b32_e32 v0, 0x1fc0, v0
	s_movk_i32 s10, 0xe000
	s_waitcnt lgkmcnt(0)
	s_add_u32 s18, s6, 0xbe00000
	v_and_or_b32 v32, v1, s10, v0
	v_lshlrev_b32_e32 v54, 3, v30
	s_addc_u32 s19, s7, 0
	v_or_b32_e32 v0, v32, v54
	s_add_u32 s8, s6, 0x14e00000
	v_or_b32_e32 v18, 2, v0
	s_addc_u32 s9, s7, 0
	v_lshlrev_b32_e32 v4, 7, v31
	v_mov_b32_e32 v5, v2
	v_mov_b64_e32 v[12:13], s[18:19]
	v_or_b32_e32 v14, 1, v0
	v_ashrrev_i32_e32 v19, 31, v18
	v_or_b32_e32 v26, 3, v0
	v_lshl_add_u64 v[6:7], s[8:9], 0, v[4:5]
	v_lshlrev_b32_e32 v22, 1, v20
	v_mov_b32_e32 v23, v2
	v_ashrrev_i32_e32 v1, 31, v0
	v_ashrrev_i32_e32 v15, 31, v14
	v_lshlrev_b64 v[24:25], 9, v[18:19]
	v_mad_i64_i32 v[18:19], s[10:11], v18, s62, v[12:13]
	v_ashrrev_i32_e32 v27, 31, v26
	v_lshl_add_u64 v[6:7], v[6:7], 0, v[22:23]
	v_lshlrev_b64 v[8:9], 9, v[0:1]
	v_mad_i64_i32 v[10:11], s[10:11], v0, s62, v[12:13]
	v_lshlrev_b64 v[16:17], 9, v[14:15]
	v_mad_i64_i32 v[14:15], s[10:11], v14, s62, v[12:13]
	v_lshl_add_u64 v[18:19], v[18:19], 0, v[4:5]
	v_lshlrev_b64 v[28:29], 9, v[26:27]
	v_mad_i64_i32 v[26:27], s[10:11], v26, s62, v[12:13]
	v_lshl_add_u64 v[8:9], v[6:7], 0, v[8:9]
	v_lshl_add_u64 v[10:11], v[10:11], 0, v[4:5]
	v_lshl_add_u64 v[14:15], v[14:15], 0, v[4:5]
	v_lshl_add_u64 v[18:19], v[18:19], 0, v[22:23]
	v_lshl_add_u64 v[28:29], v[6:7], 0, v[28:29]
	v_lshl_add_u64 v[26:27], v[26:27], 0, v[4:5]
	v_lshl_add_u64 v[10:11], v[10:11], 0, v[22:23]
	v_lshl_add_u64 v[16:17], v[6:7], 0, v[16:17]
	v_lshl_add_u64 v[14:15], v[14:15], 0, v[22:23]
	v_lshl_add_u64 v[24:25], v[6:7], 0, v[24:25]
	v_lshl_add_u64 v[26:27], v[26:27], 0, v[22:23]
	global_load_dword v34, v[8:9], off
	global_load_dword v55, v[10:11], off offset:512
	global_load_dword v35, v[16:17], off
	global_load_dword v56, v[14:15], off offset:512
	global_load_dword v41, v[24:25], off
	global_load_dword v57, v[18:19], off offset:512
	s_nop 0
	global_load_dword v28, v[28:29], off
	s_nop 0
	global_load_dword v58, v[26:27], off offset:512
	v_or_b32_e32 v8, 4, v0
	v_or_b32_e32 v18, 6, v0
	v_ashrrev_i32_e32 v9, 31, v8
	v_or_b32_e32 v14, 5, v0
	v_ashrrev_i32_e32 v19, 31, v18
	v_lshlrev_b64 v[10:11], 9, v[8:9]
	v_ashrrev_i32_e32 v15, 31, v14
	v_lshlrev_b64 v[24:25], 9, v[18:19]
	v_or_b32_e32 v0, 7, v0
	v_lshl_add_u64 v[10:11], v[6:7], 0, v[10:11]
	v_lshlrev_b64 v[16:17], 9, v[14:15]
	v_lshl_add_u64 v[24:25], v[6:7], 0, v[24:25]
	v_ashrrev_i32_e32 v1, 31, v0
	v_lshl_add_u64 v[16:17], v[6:7], 0, v[16:17]
	global_load_dword v26, v[10:11], off
	global_load_dword v27, v[16:17], off
	s_nop 0
	global_load_dword v25, v[24:25], off
	v_lshlrev_b64 v[10:11], 9, v[0:1]
	v_mad_i64_i32 v[8:9], s[10:11], v8, s62, v[12:13]
	v_lshl_add_u64 v[6:7], v[6:7], 0, v[10:11]
	v_mad_i64_i32 v[0:1], s[10:11], v0, s62, v[12:13]
	global_load_dword v29, v[6:7], off
	v_lshl_add_u64 v[6:7], v[8:9], 0, v[4:5]
	v_mad_i64_i32 v[8:9], s[10:11], v14, s62, v[12:13]
	v_mad_i64_i32 v[10:11], s[10:11], v18, s62, v[12:13]
	v_lshl_add_u64 v[0:1], v[0:1], 0, v[4:5]
	v_lshl_add_u64 v[8:9], v[8:9], 0, v[4:5]
	v_lshl_add_u64 v[10:11], v[10:11], 0, v[4:5]
	v_lshl_add_u64 v[0:1], v[0:1], 0, v[22:23]
	v_lshl_add_u64 v[6:7], v[6:7], 0, v[22:23]
	v_lshl_add_u64 v[8:9], v[8:9], 0, v[22:23]
	v_lshl_add_u64 v[10:11], v[10:11], 0, v[22:23]
	global_load_dword v71, v[0:1], off offset:512
	global_load_dword v70, v[10:11], off offset:512
	global_load_dword v69, v[8:9], off offset:512
	global_load_dword v33, v[6:7], off offset:512
	v_lshrrev_b32_e32 v0, 1, v21
	v_and_b32_e32 v24, 0x78, v0
	v_lshlrev_b32_e32 v0, 1, v21
	v_and_b32_e32 v59, 30, v0
	v_or_b32_e32 v18, v32, v59
	v_or_b32_e32 v4, 1, v18
	v_mad_i64_i32 v[0:1], s[10:11], v18, s62, v[12:13]
	v_lshlrev_b32_e32 v14, 8, v31
	v_mov_b32_e32 v15, v2
	v_mad_i64_i32 v[4:5], s[10:11], v4, s62, v[12:13]
	v_lshl_add_u64 v[0:1], v[0:1], 0, v[14:15]
	v_lshlrev_b32_e32 v16, 1, v24
	v_mov_b32_e32 v17, v2
	v_lshl_add_u64 v[4:5], v[4:5], 0, v[14:15]
	v_lshl_add_u64 v[0:1], v[0:1], 0, v[16:17]
	v_lshl_add_u64 v[8:9], v[4:5], 0, v[16:17]
	global_load_dwordx4 v[4:7], v[0:1], off offset:1024
	s_nop 0
	global_load_dwordx4 v[8:11], v[8:9], off offset:1024
	v_or_b32_e32 v0, 32, v18
	v_or_b32_e32 v18, 33, v18
	v_mad_i64_i32 v[0:1], s[10:11], v0, s62, v[12:13]
	v_mad_i64_i32 v[12:13], s[10:11], v18, s62, v[12:13]
	v_lshl_add_u64 v[0:1], v[0:1], 0, v[14:15]
	v_lshl_add_u64 v[12:13], v[12:13], 0, v[14:15]
	v_lshl_add_u64 v[0:1], v[0:1], 0, v[16:17]
	v_lshl_add_u64 v[16:17], v[12:13], 0, v[16:17]
	global_load_dwordx4 v[12:15], v[0:1], off offset:1024
	s_nop 0
	global_load_dwordx4 v[16:19], v[16:17], off offset:1024
	s_mov_b32 s10, 0xa000
	v_mad_i32_i24 v31, v3, s10, 0
	v_mul_u32_u24_e32 v1, 0x90, v20
	v_lshlrev_b32_e32 v0, 2, v20
	v_add_u32_e32 v60, v31, v0
	s_mov_b64 s[10:11], 0x3d00000
	s_movk_i32 s12, 0x9f
	s_waitcnt vmcnt(19)
	v_lshlrev_b32_e32 v36, 16, v34
	v_and_b32_e32 v37, 0xffff0000, v34
	v_and_b32_e32 v34, 15, v21
	s_waitcnt vmcnt(17)
	v_lshlrev_b32_e32 v38, 16, v35
	v_and_b32_e32 v39, 0xffff0000, v35
	s_movk_i32 s14, 0xbf
	s_waitcnt vmcnt(13)
	v_lshlrev_b32_e32 v42, 16, v28
	v_and_b32_e32 v43, 0xffff0000, v28
	v_cmp_lt_u32_sdwa s[20:21], v21, v213 src0_sel:BYTE_0 src1_sel:DWORD
	v_mul_u32_u24_e32 v32, 0x90, v24
	v_cmp_gt_u32_sdwa s[12:13], v21, s12 src0_sel:BYTE_0 src1_sel:DWORD
	v_cmp_gt_u32_sdwa s[14:15], v21, s14 src0_sel:BYTE_0 src1_sel:DWORD
	s_mov_b64 s[22:23], 0x16e00000
	v_cmp_eq_u32_e64 s[16:17], 7, v30
	v_lshlrev_b32_e32 v40, 16, v41
	v_and_b32_e32 v41, 0xffff0000, v41
	v_or_b32_e32 v63, 32, v59
	s_mov_b32 s24, s78
	s_waitcnt vmcnt(11)
	v_lshlrev_b32_e32 v44, 16, v26
	v_and_b32_e32 v45, 0xffff0000, v26
	v_lshlrev_b32_e32 v26, 4, v30
	v_add3_u32 v61, v31, v1, v26
	v_mov_b32_e32 v1, v2
	v_bfe_u32 v26, v21, 4, 2
	s_waitcnt vmcnt(10)
	v_lshlrev_b32_e32 v46, 16, v27
	v_and_b32_e32 v47, 0xffff0000, v27
	v_lshl_add_u64 v[0:1], s[6:7], 0, v[0:1]
	s_waitcnt vmcnt(8)
	v_lshlrev_b32_e32 v50, 16, v29
	v_and_b32_e32 v51, 0xffff0000, v29
	v_lshl_add_u64 v[28:29], s[8:9], 0, v[22:23]
	v_lshrrev_b32_e32 v22, 2, v21
	v_and_b32_e32 v22, 48, v22
	v_or_b32_e32 v23, v22, v34
	s_movk_i32 s8, 0x90
	v_mad_u32_u24 v35, v23, s8, v31
	v_lshlrev_b32_e32 v22, 1, v22
	v_mov_b32_e32 v23, v2
	v_lshlrev_b32_e32 v52, 4, v26
	v_lshl_add_u64 v[22:23], s[6:7], 0, v[22:23]
	v_lshlrev_b32_e32 v26, 3, v26
	v_mov_b32_e32 v27, v2
	v_lshl_add_u64 v[0:1], v[0:1], 0, s[10:11]
	v_lshl_add_u64 v[22:23], v[22:23], 0, v[26:27]
	s_movk_i32 s8, 0x5f
	s_movk_i32 s10, 0x7f
	v_lshlrev_b32_e32 v26, 7, v34
	v_cmp_gt_u32_sdwa s[6:7], v21, v214 src0_sel:BYTE_0 src1_sel:DWORD
	v_cmp_gt_u32_sdwa s[8:9], v21, s8 src0_sel:BYTE_0 src1_sel:DWORD
	v_cmp_gt_u32_sdwa s[10:11], v21, s10 src0_sel:BYTE_0 src1_sel:DWORD
	v_lshlrev_b32_e32 v21, 1, v59
	v_lshl_add_u64 v[22:23], v[22:23], 0, v[26:27]
	v_lshlrev_b32_e32 v48, 16, v25
	v_and_b32_e32 v49, 0xffff0000, v25
	v_lshlrev_b32_e32 v25, 8, v30
	v_add_u32_e32 v53, v31, v52
	v_add3_u32 v62, v31, v32, v21
	v_lshl_add_u64 v[30:31], v[22:23], 0, s[22:23]
	v_readlane_b32 s22, v254, 39
	v_mul_u32_u24_e32 v21, 0x90, v34
	v_add_u32_e32 v66, v60, v25
	v_lshl_add_u32 v64, v3, 6, s22
	v_readlane_b32 s22, v254, 41
	v_lshlrev_b32_e32 v32, 1, v20
	v_lshlrev_b32_e32 v34, 1, v24
	v_lshl_add_u32 v65, v3, 4, s22
	v_add_u32_e32 v67, v35, v52
	v_add_u32_e32 v68, v53, v21
	s_branch .LBB0_419

.LBB0_516:
	s_or_b64 exec, exec, s[6:7]
	s_waitcnt lgkmcnt(0)
	s_add_u32 s20, s8, 0xbe00000
	v_readlane_b32 s12, v254, 7
	s_addc_u32 s21, s9, 0
	v_lshlrev_b32_e32 v24, 1, v0
	v_readlane_b32 s13, v254, 8
	s_add_u32 s10, s8, 0x14e00000
	v_and_b32_e32 v20, 62, v24
	s_waitcnt vmcnt(11)
	v_cndmask_b32_e64 v4, 0, 1, s[12:13]
	v_ashrrev_i32_e32 v157, 8, v0
	s_addc_u32 s11, s9, 0
	v_lshrrev_b32_sdwa v1, v217, v0 dst_sel:DWORD dst_unused:UNUSED_PAD src0_sel:DWORD src1_sel:BYTE_0
	v_cmp_ne_u32_e64 s[6:7], 1, v4
	s_andn2_b64 vcc, exec, s[12:13]
	v_lshlrev_b32_e32 v22, 1, v20
	v_lshrrev_b32_e32 v21, 3, v0
	s_barrier
	s_cbranch_vccnz .LBB0_518
	v_add_u32_e32 v4, s94, v157
	v_bfe_u32 v25, v4, 7, 2
	v_lshlrev_b32_e32 v5, 4, v4
	v_lshlrev_b32_e32 v4, 6, v4
	v_and_b32_e32 v4, 0x1fc0, v4
	s_movk_i32 s12, 0xe000
	v_and_or_b32 v32, v5, s12, v4
	v_lshl_or_b32 v4, v1, 3, v32
	s_waitcnt vmcnt(8)
	v_or_b32_e32 v16, 1, v4
	v_lshlrev_b32_e32 v6, 7, v25
	v_mov_b32_e32 v7, v2
	v_mov_b64_e32 v[12:13], s[20:21]
	v_ashrrev_i32_e32 v17, 31, v16
	v_or_b32_e32 v26, 2, v4
	v_lshl_add_u64 v[8:9], s[10:11], 0, v[6:7]
	v_mov_b32_e32 v23, v2
	v_ashrrev_i32_e32 v5, 31, v4
	v_lshlrev_b64 v[18:19], 9, v[16:17]
	v_mad_i64_i32 v[16:17], s[12:13], v16, s62, v[12:13]
	v_ashrrev_i32_e32 v27, 31, v26
	v_lshl_add_u64 v[8:9], v[8:9], 0, v[22:23]
	v_lshlrev_b64 v[10:11], 9, v[4:5]
	v_mad_i64_i32 v[14:15], s[12:13], v4, s62, v[12:13]
	v_lshl_add_u64 v[16:17], v[16:17], 0, v[6:7]
	v_lshlrev_b64 v[28:29], 9, v[26:27]
	v_mad_i64_i32 v[26:27], s[12:13], v26, s62, v[12:13]
	v_lshl_add_u64 v[10:11], v[8:9], 0, v[10:11]
	v_lshl_add_u64 v[14:15], v[14:15], 0, v[6:7]
	v_lshl_add_u64 v[16:17], v[16:17], 0, v[22:23]
	v_lshl_add_u64 v[26:27], v[26:27], 0, v[6:7]
	v_lshl_add_u64 v[14:15], v[14:15], 0, v[22:23]
	v_lshl_add_u64 v[18:19], v[8:9], 0, v[18:19]
	v_lshl_add_u64 v[28:29], v[8:9], 0, v[28:29]
	v_lshl_add_u64 v[26:27], v[26:27], 0, v[22:23]
	global_load_dword v33, v[10:11], off
	global_load_dword v220, v[14:15], off
	global_load_dword v219, v[14:15], off offset:512
	global_load_dword v34, v[18:19], off
	global_load_dword v222, v[16:17], off
	global_load_dword v221, v[16:17], off offset:512
	global_load_dword v35, v[28:29], off
	global_load_dword v223, v[26:27], off
	v_or_b32_e32 v10, 3, v4
	v_or_b32_e32 v16, 4, v4
	v_ashrrev_i32_e32 v11, 31, v10
	v_ashrrev_i32_e32 v17, 31, v16
	v_or_b32_e32 v28, 5, v4
	v_lshlrev_b64 v[14:15], 9, v[10:11]
	v_mad_i64_i32 v[10:11], s[12:13], v10, s62, v[12:13]
	v_lshlrev_b64 v[18:19], 9, v[16:17]
	v_mad_i64_i32 v[16:17], s[12:13], v16, s62, v[12:13]
	v_ashrrev_i32_e32 v29, 31, v28
	v_lshl_add_u64 v[14:15], v[8:9], 0, v[14:15]
	v_lshl_add_u64 v[10:11], v[10:11], 0, v[6:7]
	v_lshl_add_u64 v[16:17], v[16:17], 0, v[6:7]
	v_lshlrev_b64 v[30:31], 9, v[28:29]
	v_lshl_add_u64 v[10:11], v[10:11], 0, v[22:23]
	v_lshl_add_u64 v[18:19], v[8:9], 0, v[18:19]
	v_lshl_add_u64 v[16:17], v[16:17], 0, v[22:23]
	v_lshl_add_u64 v[30:31], v[8:9], 0, v[30:31]
	global_load_dword v224, v[26:27], off offset:512
	s_nop 0
	global_load_dword v26, v[14:15], off
	global_load_dword v226, v[10:11], off
	global_load_dword v225, v[10:11], off offset:512
	global_load_dword v27, v[18:19], off
	global_load_dword v228, v[16:17], off
	global_load_dword v227, v[16:17], off offset:512
	global_load_dword v29, v[30:31], off
	v_or_b32_e32 v14, 6, v4
	v_ashrrev_i32_e32 v15, 31, v14
	v_or_b32_e32 v4, 7, v4
	v_mad_i64_i32 v[10:11], s[12:13], v28, s62, v[12:13]
	v_lshlrev_b64 v[16:17], 9, v[14:15]
	v_mad_i64_i32 v[14:15], s[12:13], v14, s62, v[12:13]
	v_ashrrev_i32_e32 v5, 31, v4
	v_lshl_add_u64 v[10:11], v[10:11], 0, v[6:7]
	v_lshl_add_u64 v[14:15], v[14:15], 0, v[6:7]
	v_lshlrev_b64 v[18:19], 9, v[4:5]
	v_mad_i64_i32 v[4:5], s[12:13], v4, s62, v[12:13]
	v_lshl_add_u64 v[10:11], v[10:11], 0, v[22:23]
	v_lshl_add_u64 v[16:17], v[8:9], 0, v[16:17]
	v_lshl_add_u64 v[14:15], v[14:15], 0, v[22:23]
	v_lshl_add_u64 v[4:5], v[4:5], 0, v[6:7]
	v_lshlrev_b32_e32 v30, 1, v0
	v_and_or_b32 v30, v30, 30, v32
	v_lshlrev_b32_e32 v6, 4, v0
	v_lshl_add_u64 v[8:9], v[8:9], 0, v[18:19]
	v_lshl_add_u64 v[4:5], v[4:5], 0, v[22:23]
	global_load_dword v229, v[10:11], off
	global_load_dword v201, v[10:11], off offset:512
	global_load_dword v23, v[16:17], off
	global_load_dword v231, v[14:15], off
	global_load_dword v230, v[14:15], off offset:512
	global_load_dword v28, v[8:9], off
	global_load_dword v233, v[4:5], off
	global_load_dword v232, v[4:5], off offset:512
	v_lshlrev_b32_e32 v14, 8, v25
	v_and_b32_e32 v16, 0xf0, v0
	v_or_b32_e32 v6, 1, v30
	v_or_b32_e32 v18, 32, v30
	v_or_b32_e32 v25, 33, v30
	v_mad_i64_i32 v[4:5], s[12:13], v30, s62, v[12:13]
	v_mov_b32_e32 v15, v2
	v_mad_i64_i32 v[6:7], s[12:13], v6, s62, v[12:13]
	v_mad_i64_i32 v[18:19], s[12:13], v18, s62, v[12:13]
	v_mad_i64_i32 v[12:13], s[12:13], v25, s62, v[12:13]
	v_lshl_add_u64 v[4:5], v[4:5], 0, v[14:15]
	v_mov_b32_e32 v17, v2
	v_lshl_add_u64 v[6:7], v[6:7], 0, v[14:15]
	v_lshl_add_u64 v[18:19], v[18:19], 0, v[14:15]
	v_lshl_add_u64 v[12:13], v[12:13], 0, v[14:15]
	v_lshl_add_u64 v[4:5], v[4:5], 0, v[16:17]
	v_lshl_add_u64 v[8:9], v[6:7], 0, v[16:17]
	v_lshl_add_u64 v[18:19], v[18:19], 0, v[16:17]
	v_lshl_add_u64 v[16:17], v[12:13], 0, v[16:17]
	global_load_dwordx4 v[4:7], v[4:5], off offset:1024
	s_nop 0
	global_load_dwordx4 v[8:11], v[8:9], off offset:1024
	s_nop 0
	global_load_dwordx4 v[12:15], v[18:19], off offset:1024
	s_nop 0
	global_load_dwordx4 v[16:19], v[16:17], off offset:1024
	s_waitcnt vmcnt(27)
	v_lshlrev_b32_e32 v152, 16, v33
	v_and_b32_e32 v153, 0xffff0000, v33
	s_waitcnt vmcnt(24)
	v_lshlrev_b32_e32 v154, 16, v34
	v_and_b32_e32 v155, 0xffff0000, v34
	s_waitcnt vmcnt(21)
	v_lshlrev_b32_e32 v170, 16, v35
	v_and_b32_e32 v171, 0xffff0000, v35
	s_waitcnt vmcnt(18)
	v_lshlrev_b32_e32 v172, 16, v26
	v_and_b32_e32 v173, 0xffff0000, v26
	s_waitcnt vmcnt(15)
	v_lshlrev_b32_e32 v174, 16, v27
	v_and_b32_e32 v175, 0xffff0000, v27
	s_waitcnt vmcnt(12)
	v_lshlrev_b32_e32 v176, 16, v29
	v_and_b32_e32 v177, 0xffff0000, v29
	s_waitcnt vmcnt(9)
	v_lshlrev_b32_e32 v178, 16, v23
	v_and_b32_e32 v179, 0xffff0000, v23
	s_waitcnt vmcnt(6)
	v_lshlrev_b32_e32 v180, 16, v28
	v_and_b32_e32 v181, 0xffff0000, v28
.LBB0_518:
	s_and_b64 vcc, exec, s[6:7]
	s_cbranch_vccnz .LBB0_554
	s_add_u32 s22, s8, 0x7e00000
	v_bfe_u32 v33, v0, 4, 2
	s_addc_u32 s23, s9, 0
	v_and_b32_e32 v23, 3, v0
	v_lshlrev_b32_e32 v26, 4, v33
	v_mov_b32_e32 v27, v2
	v_lshl_add_u32 v25, v157, 16, 0
	v_and_or_b32 v35, v24, 24, v23
	v_lshl_add_u64 v[28:29], s[8:9], 0, v[26:27]
	s_mov_b64 s[6:7], 0x1ae00000
	v_lshlrev_b32_e32 v23, 3, v0
	s_cmp_gt_i32 s16, -1
	v_lshl_add_u32 v234, v20, 2, v25
	v_and_b32_e32 v31, 15, v0
	v_lshl_add_u64 v[148:149], v[28:29], 0, s[6:7]
	v_lshrrev_b32_e32 v28, 1, v208
	v_and_b32_e32 v28, 0x78, v28
	v_mov_b32_e32 v23, v2
	v_and_b32_e32 v30, 64, v211
	s_cselect_b64 s[38:39], -1, 0
	s_cmp_eq_u32 s16, 0
	v_lshl_or_b32 v235, v3, 4, v31
	v_sub_u32_e32 v27, v234, v22
	v_lshl_add_u64 v[150:151], s[10:11], 0, v[22:23]
	s_movk_i32 s6, 0x90
	v_xor_b32_e32 v22, 16, v211
	v_add_u32_e32 v30, 64, v30
	s_cselect_b64 s[40:41], -1, 0
	s_cmp_gt_i32 s16, 0
	v_mad_u32_u24 v23, v235, s6, v25
	v_cmp_lt_i32_e32 vcc, v22, v30
	s_movk_i32 s6, 0x5f
	s_cselect_b64 s[42:43], -1, 0
	s_cmp_eq_u32 s16, 1
	v_cndmask_b32_e32 v22, v211, v22, vcc
	v_cmp_gt_u32_sdwa s[28:29], v0, s6 src0_sel:BYTE_0 src1_sel:DWORD
	s_movk_i32 s6, 0x7f
	s_cselect_b64 s[44:45], -1, 0
	s_cmp_gt_i32 s16, 1
	v_lshlrev_b32_e32 v237, 2, v22
	v_xor_b32_e32 v22, 32, v211
	v_cmp_gt_u32_sdwa s[30:31], v0, s6 src0_sel:BYTE_0 src1_sel:DWORD
	s_movk_i32 s6, 0x9f
	s_cselect_b64 s[46:47], -1, 0
	s_cmp_eq_u32 s16, 2
	v_lshlrev_b32_e32 v39, 2, v33
	v_cmp_lt_i32_e32 vcc, v22, v30
	v_cmp_gt_u32_sdwa s[34:35], v0, s6 src0_sel:BYTE_0 src1_sel:DWORD
	s_movk_i32 s6, 0xbf
	s_cselect_b64 s[48:49], -1, 0
	s_cmp_gt_i32 s16, 2
	v_lshlrev_b32_e32 v3, 8, v1
	v_lshlrev_b32_e32 v236, 3, v1
	v_cndmask_b32_e32 v22, v211, v22, vcc
	v_cmp_gt_u32_sdwa s[24:25], v0, v218 src0_sel:BYTE_0 src1_sel:DWORD
	v_cmp_gt_u32_sdwa s[26:27], v0, v214 src0_sel:BYTE_0 src1_sel:DWORD
	v_cmp_gt_u32_sdwa s[36:37], v0, s6 src0_sel:BYTE_0 src1_sel:DWORD
	v_cmp_eq_u32_e64 s[6:7], 7, v1
	v_mul_u32_u24_e32 v0, 0x240, v1
	v_lshlrev_b32_e32 v240, 1, v208
	v_and_b32_e32 v240, 30, v240
	v_or_b32_e32 v1, 2, v39
	s_cselect_b64 s[50:51], -1, 0
	s_cmp_eq_u32 s16, 3
	v_lshlrev_b32_e32 v24, 3, v33
	v_mul_u32_u24_e32 v29, 0x90, v28
	v_lshlrev_b32_e32 v238, 2, v22
	v_lshlrev_b32_e32 v22, 6, v35
	v_lshl_add_u32 v239, v0, 1, v27
	v_lshlrev_b32_e32 v0, 1, v240
	v_cmp_gt_u32_e64 s[12:13], v1, v31
	v_or_b32_e32 v1, 3, v39
	s_cselect_b64 s[52:53], -1, 0
	s_add_i32 s16, 0, 0x20000
	v_add_u32_e32 v37, v25, v26
	v_add_u32_e32 v41, v25, v24
	v_or_b32_e32 v30, 0x100, v22
	v_or_b32_e32 v32, 0x800, v22
	v_or_b32_e32 v34, 0x900, v22
	v_or_b32_e32 v36, 0x1000, v22
	v_or_b32_e32 v38, 0x1100, v22
	v_or_b32_e32 v40, 0x1800, v22
	v_or_b32_e32 v42, 0x1900, v22
	v_add3_u32 v241, v25, v29, v0
	v_mul_u32_u24_e32 v0, 0x90, v31
	v_cmp_gt_u32_e64 s[14:15], v1, v31
	v_mul_u32_u24_e32 v1, 0x90, v35
	v_lshl_add_u32 v243, v33, 5, s16
	v_or_b32_e32 v242, 32, v240
	v_cmp_gt_u32_e64 s[8:9], v39, v31
	v_cmp_lt_u32_e64 s[10:11], v39, v31
	v_add_u32_e32 v244, 0x80, v243
	v_add_u32_e32 v245, 0x100, v243
	v_add_u32_e32 v246, 0x180, v243
	v_lshlrev_b32_e32 v247, 6, v157
	v_lshlrev_b32_e32 v248, 4, v157
	v_lshlrev_b32_e32 v182, 1, v24
	v_lshlrev_b32_e32 v184, 1, v22
	v_lshlrev_b32_e32 v186, 1, v30
	v_lshlrev_b32_e32 v188, 1, v32
	v_lshlrev_b32_e32 v190, 1, v34
	v_lshlrev_b32_e32 v192, 1, v36
	v_lshlrev_b32_e32 v194, 1, v38
	v_lshlrev_b32_e32 v196, 1, v40
	v_lshlrev_b32_e32 v198, 1, v42
	v_add_u32_e32 v249, v234, v3
	v_lshlrev_b32_e32 v200, 1, v20
	v_lshlrev_b32_e32 v202, 1, v28
	v_add_u32_e32 v250, v23, v26
	v_add_u32_e32 v251, v37, v0
	v_add_u32_e32 v252, v41, v1
	s_mov_b32 s56, s78
	s_branch .LBB0_522
